# layer-1 weight conversion (all but w_ffn_down) moved into idle WGs of layer-0 phase-J third round
# speedup vs baseline: 1.0113x; 1.0113x over previous
.LBB0_91:
	s_or_b64 exec, exec, s[0:1]
	v_readlane_b32 s18, v255, 8
	v_readlane_b32 s19, v255, 9
	s_load_dwordx4 s[56:59], s[18:19], 0xd8
	s_nop 0
	s_load_dwordx2 s[18:19], s[18:19], 0xf0
	s_waitcnt lgkmcnt(0)

.Lcv_wd_done:
	s_barrier
	s_mov_b64 s[0:1], 0

.LBB0_1000:
	s_waitcnt vmcnt(0)
	s_barrier
	v_readlane_b32 s83, v255, 41
	s_cmp_lg_u32 s83, 0
	s_cbranch_scc1 .LBB0_1001
	s_cmp_gt_u32 s60, 64
	s_cselect_b32 s84, 64, 0
	s_cmp_lt_u32 s2, s84
	s_cbranch_scc1 .LBB0_1001
	s_sub_u32 s2, s2, s84
	s_sub_u32 s60, s60, s84
	v_writelane_b32 v255, s84, 47
	v_readlane_b32 s62, v255, 37
	v_readlane_b32 s63, v255, 38
	v_readlane_b32 s18, v255, 8
	v_readlane_b32 s19, v255, 9
	s_load_dwordx4 s[48:51], s[18:19], 0x48
	s_load_dwordx2 s[0:1], s[18:19], 0x68
	s_load_dwordx2 s[38:39], s[18:19], 0x88
	s_load_dwordx2 s[22:23], s[18:19], 0x98
	s_load_dwordx8 s[40:47], s[18:19], 0xb8
	s_load_dwordx4 s[56:59], s[18:19], 0xd8
	s_nop 0
	s_load_dwordx2 s[18:19], s[18:19], 0xf0
	v_mov_b32_e32 v0, v208
	s_mov_b32 s24, s2
	s_cmpk_gt_i32 s24, 0x3ff
	s_cbranch_scc1 .LBB0_96
	s_waitcnt lgkmcnt(0)
	s_add_u32 s48, s48, 0x2000000
	s_addc_u32 s49, s49, 0
	s_ashr_i32 s26, s24, 31
	s_lshr_b32 s26, s26, 28
	s_add_i32 s26, s24, s26
	s_lshl_b32 s27, s26, 2
	s_and_b32 s26, s26, 0x1fffff0
	v_ashrrev_i32_e32 v23, 6, v0
	s_sub_i32 s26, s24, s26
	v_mov_b32_e32 v1, s27
	s_movk_i32 s27, 0xffc0
	v_bfi_b32 v2, s27, v1, v0
	v_lshl_add_u32 v4, s26, 7, v23
	v_ashrrev_i32_e32 v3, 31, v2
	v_ashrrev_i32_e32 v5, 31, v4
	v_lshl_add_u64 v[2:3], v[2:3], 2, s[48:49]
	v_lshlrev_b64 v[4:5], 14, v[4:5]
	v_lshl_add_u64 v[2:3], v[2:3], 0, v[4:5]
	v_add_co_u32_e32 v4, vcc, s17, v2
	s_mov_b32 s26, 0xe0000
	s_nop 0
	v_addc_co_u32_e32 v5, vcc, 0, v3, vcc
	v_add_co_u32_e32 v6, vcc, s20, v2
	v_and_b32_e32 v20, 63, v0
	s_nop 0
	v_addc_co_u32_e32 v7, vcc, 0, v3, vcc
	v_add_co_u32_e32 v8, vcc, s21, v2
	v_ashrrev_i32_e32 v21, 4, v0
	s_nop 0
	v_addc_co_u32_e32 v9, vcc, 0, v3, vcc
	v_add_co_u32_e32 v10, vcc, s64, v2
	v_lshlrev_b32_e32 v0, 3, v0
	s_waitcnt vmcnt(6)
	v_addc_co_u32_e32 v11, vcc, 0, v3, vcc
	s_waitcnt vmcnt(5)
	v_add_co_u32_e32 v12, vcc, s65, v2
	v_and_b32_e32 v22, 0x78, v0
	s_waitcnt vmcnt(4)
	v_addc_co_u32_e32 v13, vcc, 0, v3, vcc
	v_add_co_u32_e32 v14, vcc, s66, v2
	s_waitcnt vmcnt(3)
	v_lshlrev_b32_e32 v16, 1, v22
	s_waitcnt vmcnt(2)
	v_addc_co_u32_e32 v15, vcc, 0, v3, vcc
	v_add_co_u32_e32 v24, vcc, s26, v2
	s_mov_b32 s26, 0x100000
	s_nop 0
	v_addc_co_u32_e32 v25, vcc, 0, v3, vcc
	v_add_co_u32_e32 v26, vcc, s26, v2
	s_mov_b32 s26, 0x120000
	s_nop 0
	v_addc_co_u32_e32 v27, vcc, 0, v3, vcc
	v_add_co_u32_e32 v28, vcc, s26, v2
	s_mov_b32 s26, 0x140000
	s_nop 0
	v_addc_co_u32_e32 v29, vcc, 0, v3, vcc
	v_add_co_u32_e32 v30, vcc, s26, v2
	s_mov_b32 s26, 0x160000
	s_nop 0
	v_addc_co_u32_e32 v31, vcc, 0, v3, vcc
	v_add_co_u32_e32 v32, vcc, s26, v2
	s_mov_b32 s26, 0x180000
	s_nop 0
	v_addc_co_u32_e32 v33, vcc, 0, v3, vcc
	v_add_co_u32_e32 v34, vcc, s26, v2
	s_mov_b32 s26, 0x1a0000
	s_nop 0
	v_addc_co_u32_e32 v35, vcc, 0, v3, vcc
	v_add_co_u32_e32 v36, vcc, s26, v2
	s_mov_b32 s26, 0x1c0000
	s_nop 0
	v_addc_co_u32_e32 v37, vcc, 0, v3, vcc
	v_add_co_u32_e32 v38, vcc, s26, v2
	s_mov_b32 s26, 0x1e0000
	s_nop 0
	v_addc_co_u32_e32 v39, vcc, 0, v3, vcc
	v_add_co_u32_e32 v40, vcc, s26, v2
	v_lshl_add_u64 v[0:1], s[18:19], 0, v[16:17]
	s_mov_b64 s[26:27], 0x378000
	v_addc_co_u32_e32 v41, vcc, 0, v3, vcc
	v_lshl_add_u64 v[18:19], v[0:1], 0, s[26:27]
	global_load_dword v0, v[2:3], off
	global_load_dword v1, v[4:5], off
	s_nop 0
	global_load_dword v2, v[6:7], off
	global_load_dword v3, v[8:9], off
	global_load_dword v4, v[10:11], off
	global_load_dword v5, v[12:13], off
	s_nop 0
	global_load_dword v6, v[14:15], off
	global_load_dword v7, v[24:25], off
	global_load_dword v8, v[26:27], off
	global_load_dword v9, v[28:29], off
	global_load_dword v10, v[30:31], off
	global_load_dword v11, v[32:33], off
	global_load_dword v12, v[34:35], off
	global_load_dword v13, v[36:37], off
	global_load_dword v14, v[38:39], off
	global_load_dword v15, v[40:41], off
	s_movk_i32 s26, 0x104
	s_lshl_b32 s27, s60, 7
	v_mul_lo_u32 v16, v23, s26
	v_mul_u32_u24_e32 v22, 0x104, v22
	s_lshl_b32 s26, s24, 7
	v_add_u32_e32 v23, s27, v23
	s_mov_b64 s[52:53], 0
	s_branch .LBB0_94

.LBB0_108:
	s_waitcnt vmcnt(17)
	v_mov_b32_e32 v0, v208
	s_mov_b32 s24, s2
	s_cmpk_gt_i32 s24, 0x1ff
	s_cbranch_scc1 .LBB0_113
	s_add_u32 s40, s44, 0x1000000
	s_addc_u32 s41, s45, 0
	s_ashr_i32 s26, s24, 31
	s_lshr_b32 s26, s26, 28
	s_add_i32 s26, s24, s26
	s_lshl_b32 s27, s26, 2
	s_and_b32 s26, s26, 0x1fffff0
	v_ashrrev_i32_e32 v23, 6, v0
	s_sub_i32 s26, s24, s26
	s_waitcnt vmcnt(16)
	v_mov_b32_e32 v1, s27
	s_movk_i32 s27, 0xffc0
	s_waitcnt vmcnt(15)
	v_bfi_b32 v2, s27, v1, v0
	s_waitcnt vmcnt(13)
	v_lshl_add_u32 v4, s26, 7, v23
	v_ashrrev_i32_e32 v3, 31, v2
	s_waitcnt vmcnt(12)
	v_ashrrev_i32_e32 v5, 31, v4
	v_lshl_add_u64 v[2:3], v[2:3], 2, s[40:41]
	v_lshlrev_b64 v[4:5], 13, v[4:5]
	v_lshl_add_u64 v[2:3], v[2:3], 0, v[4:5]
	v_add_co_u32_e32 v4, vcc, s67, v2
	s_mov_b32 s26, 0xb0000
	s_nop 0
	v_addc_co_u32_e32 v5, vcc, 0, v3, vcc
	s_waitcnt vmcnt(11)
	v_add_co_u32_e32 v6, vcc, s17, v2
	v_and_b32_e32 v20, 63, v0
	s_waitcnt vmcnt(10)
	v_addc_co_u32_e32 v7, vcc, 0, v3, vcc
	s_waitcnt vmcnt(9)
	v_add_co_u32_e32 v8, vcc, s74, v2
	v_ashrrev_i32_e32 v21, 4, v0
	s_waitcnt vmcnt(8)
	v_addc_co_u32_e32 v9, vcc, 0, v3, vcc
	s_waitcnt vmcnt(7)
	v_add_co_u32_e32 v10, vcc, s20, v2
	s_mov_b32 s27, 0xf0000
	s_waitcnt vmcnt(6)
	v_addc_co_u32_e32 v11, vcc, 0, v3, vcc
	s_waitcnt vmcnt(5)
	v_add_co_u32_e32 v12, vcc, s75, v2
	v_lshlrev_b32_e32 v0, 3, v0
	s_waitcnt vmcnt(4)
	v_addc_co_u32_e32 v13, vcc, 0, v3, vcc
	s_waitcnt vmcnt(3)
	v_add_co_u32_e32 v14, vcc, s21, v2
	v_and_b32_e32 v22, 0x78, v0
	s_waitcnt vmcnt(2)
	v_addc_co_u32_e32 v15, vcc, 0, v3, vcc
	v_add_co_u32_e32 v24, vcc, s30, v2
	v_lshlrev_b32_e32 v16, 1, v22
	s_nop 0
	v_addc_co_u32_e32 v25, vcc, 0, v3, vcc
	v_add_co_u32_e32 v26, vcc, s64, v2
	v_lshl_add_u64 v[0:1], s[18:19], 0, v[16:17]
	s_nop 0
	v_addc_co_u32_e32 v27, vcc, 0, v3, vcc
	v_add_co_u32_e32 v28, vcc, s31, v2
	v_mul_u32_u24_e32 v22, 0x104, v22
	s_nop 0
	v_addc_co_u32_e32 v29, vcc, 0, v3, vcc
	v_add_co_u32_e32 v30, vcc, s65, v2
	s_mov_b64 s[42:43], 0
	s_nop 0
	v_addc_co_u32_e32 v31, vcc, 0, v3, vcc
	v_add_co_u32_e32 v32, vcc, s26, v2
	s_mov_b32 s26, 0xd0000
	s_nop 0
	v_addc_co_u32_e32 v33, vcc, 0, v3, vcc
	v_add_co_u32_e32 v34, vcc, s66, v2
	s_nop 1
	v_addc_co_u32_e32 v35, vcc, 0, v3, vcc
	v_add_co_u32_e32 v36, vcc, s26, v2
	s_mov_b32 s26, 0xe0000
	s_nop 0
	v_addc_co_u32_e32 v37, vcc, 0, v3, vcc
	v_add_co_u32_e32 v38, vcc, s26, v2
	s_load_dword s28, s[62:63], 0x0
	s_load_dword s26, s[62:63], 0x10
	v_addc_co_u32_e32 v39, vcc, 0, v3, vcc
	v_add_co_u32_e32 v40, vcc, s27, v2
	s_waitcnt lgkmcnt(0)
	s_lshr_b32 s26, s26, 16
	s_cmp_lg_u32 s26, 0
	s_cselect_b64 s[26:27], -1, 0
	s_cmp_lg_u64 s[26:27], 0
	s_addc_u32 s26, s28, 0
	s_mov_b32 s26, s60
	s_mov_b64 s[28:29], 0x3b78000
	v_addc_co_u32_e32 v41, vcc, 0, v3, vcc
	v_lshl_add_u64 v[18:19], v[0:1], 0, s[28:29]
	global_load_dword v0, v[2:3], off
	global_load_dword v1, v[4:5], off
	s_nop 0
	global_load_dword v2, v[6:7], off
	global_load_dword v3, v[8:9], off
	global_load_dword v4, v[10:11], off
	global_load_dword v5, v[12:13], off
	s_nop 0
	global_load_dword v6, v[14:15], off
	global_load_dword v7, v[24:25], off
	global_load_dword v8, v[26:27], off
	global_load_dword v9, v[28:29], off
	global_load_dword v10, v[30:31], off
	global_load_dword v11, v[32:33], off
	global_load_dword v12, v[34:35], off
	global_load_dword v13, v[36:37], off
	global_load_dword v14, v[38:39], off
	global_load_dword v15, v[40:41], off
	s_movk_i32 s27, 0x104
	s_lshl_b32 s36, s26, 7
	v_mul_lo_u32 v16, v23, s27
	s_lshl_b32 s27, s24, 7
	v_add_u32_e32 v23, s36, v23
	s_branch .LBB0_111

.LBB0_113:
	s_waitcnt vmcnt(17)
	v_mov_b32_e32 v0, v208
	s_mov_b32 s37, s2
	s_barrier
	s_cmpk_gt_i32 s37, 0xaff
	s_cbranch_scc1 .Lcv_after_gu
	s_add_u32 s24, s46, 0x2c00000
	s_addc_u32 s26, s47, 0
	s_add_u32 s27, s56, 0x2c00000
	s_addc_u32 s36, s57, 0
	s_ashr_i32 s28, s37, 31
	s_lshr_b32 s28, s28, 28
	s_add_i32 s28, s37, s28
	s_ashr_i32 s29, s28, 4
	s_and_b32 s28, s28, 0x1fffff0
	s_lshl_b32 s40, s29, 6
	s_sub_i32 s41, s37, s28
	s_bitcmp0_b32 s29, 1
	s_cselect_b32 s42, s26, s36
	s_cselect_b32 s43, s24, s27
	s_ashr_i32 s28, s40, 1
	s_and_b32 s28, s28, 0xffffff80
	s_ashr_i32 s29, s28, 31
	v_and_b32_e32 v20, 63, v0
	s_lshl_b64 s[28:29], s[28:29], 2
	s_add_u32 s28, s43, s28
	s_waitcnt vmcnt(16)
	v_and_or_b32 v1, s40, 64, v20
	v_ashrrev_i32_e32 v24, 6, v0
	s_addc_u32 s29, s42, s29
	s_waitcnt vmcnt(3)
	v_lshlrev_b32_e32 v16, 2, v1
	v_lshl_add_u64 v[2:3], s[28:29], 0, v[16:17]
	v_lshl_add_u32 v1, s41, 7, v24
	s_movk_i32 s28, 0x5800
	v_mad_i64_i32 v[2:3], s[28:29], v1, s28, v[2:3]
	s_mov_b32 s28, 0x2c000
	s_nop 0
	v_add_co_u32_e32 v4, vcc, s28, v2
	s_mov_b32 s28, 0x58000
	s_nop 0
	v_addc_co_u32_e32 v5, vcc, 0, v3, vcc
	v_add_co_u32_e32 v6, vcc, s28, v2
	s_mov_b32 s28, 0x84000
	s_nop 0
	v_addc_co_u32_e32 v7, vcc, 0, v3, vcc
	v_add_co_u32_e32 v8, vcc, s28, v2
	s_mov_b32 s28, 0xb0000
	s_nop 0
	v_addc_co_u32_e32 v9, vcc, 0, v3, vcc
	v_add_co_u32_e32 v10, vcc, s28, v2
	s_mov_b32 s28, 0xdc000
	s_nop 0
	v_addc_co_u32_e32 v11, vcc, 0, v3, vcc
	v_add_co_u32_e32 v12, vcc, s28, v2
	s_mov_b32 s28, 0x108000
	s_nop 0
	v_addc_co_u32_e32 v13, vcc, 0, v3, vcc
	v_add_co_u32_e32 v14, vcc, s28, v2
	s_mov_b32 s28, 0x134000
	s_waitcnt vmcnt(2)
	v_addc_co_u32_e32 v15, vcc, 0, v3, vcc
	v_add_co_u32_e32 v26, vcc, s28, v2
	s_mov_b32 s28, 0x160000
	s_nop 0
	v_addc_co_u32_e32 v27, vcc, 0, v3, vcc
	v_add_co_u32_e32 v28, vcc, s28, v2
	s_mov_b32 s28, 0x18c000
	s_nop 0
	v_addc_co_u32_e32 v29, vcc, 0, v3, vcc
	v_add_co_u32_e32 v30, vcc, s28, v2
	s_mov_b32 s28, 0x1b8000
	s_nop 0
	v_addc_co_u32_e32 v31, vcc, 0, v3, vcc
	v_add_co_u32_e32 v32, vcc, s28, v2
	s_mov_b32 s28, 0x1e4000
	s_nop 0
	v_addc_co_u32_e32 v33, vcc, 0, v3, vcc
	v_add_co_u32_e32 v34, vcc, s28, v2
	s_mov_b32 s28, 0x210000
	s_nop 0
	v_addc_co_u32_e32 v35, vcc, 0, v3, vcc
	v_add_co_u32_e32 v36, vcc, s28, v2
	s_mov_b32 s28, 0x23c000
	s_nop 0
	v_addc_co_u32_e32 v37, vcc, 0, v3, vcc
	v_add_co_u32_e32 v38, vcc, s28, v2
	s_mov_b32 s28, 0x268000
	s_nop 0
	v_addc_co_u32_e32 v39, vcc, 0, v3, vcc
	v_add_co_u32_e32 v40, vcc, s28, v2
	s_load_dword s40, s[62:63], 0x0
	s_load_dword s28, s[62:63], 0x10
	v_ashrrev_i32_e32 v21, 4, v0
	v_lshlrev_b32_e32 v0, 3, v0
	v_addc_co_u32_e32 v41, vcc, 0, v3, vcc
	s_waitcnt lgkmcnt(0)
	s_lshr_b32 s28, s28, 16
	s_mov_b32 s29, 0x294000
	s_cmp_lg_u32 s28, 0
	v_and_b32_e32 v23, 0x78, v0
	v_add_co_u32_e32 v42, vcc, s29, v2
	s_cselect_b64 s[28:29], -1, 0
	v_lshlrev_b32_e32 v16, 1, v23
	s_cmp_lg_u64 s[28:29], 0
	v_lshl_add_u64 v[0:1], s[18:19], 0, v[16:17]
	s_mov_b64 s[28:29], 0x4378000
	v_addc_co_u32_e32 v43, vcc, 0, v3, vcc
	v_lshl_add_u64 v[18:19], v[0:1], 0, s[28:29]
	global_load_dword v0, v[2:3], off
	global_load_dword v1, v[4:5], off
	s_nop 0
	global_load_dword v2, v[6:7], off
	global_load_dword v3, v[8:9], off
	global_load_dword v4, v[10:11], off
	global_load_dword v5, v[12:13], off
	s_nop 0
	global_load_dword v6, v[14:15], off
	global_load_dword v7, v[26:27], off
	global_load_dword v8, v[28:29], off
	global_load_dword v9, v[30:31], off
	global_load_dword v10, v[32:33], off
	global_load_dword v11, v[34:35], off
	global_load_dword v12, v[36:37], off
	global_load_dword v13, v[38:39], off
	global_load_dword v14, v[40:41], off
	global_load_dword v15, v[42:43], off
	s_addc_u32 s42, s40, 0
	s_mov_b32 s42, s60
	s_movk_i32 s28, 0x104
	s_lshl_b32 s44, s42, 7
	v_mul_lo_u32 v22, v24, s28
	v_mul_u32_u24_e32 v23, 0x104, v23
	s_lshl_b32 s43, s37, 7
	v_add_u32_e32 v24, s44, v24
	s_mov_b64 s[40:41], 0
	s_branch .LBB0_116

.Lcv_after_gu:
	s_waitcnt vmcnt(17)
	s_barrier

.LBB0_147:
	s_or_b64 exec, exec, s[22:23]
	v_readlane_b32 s84, v255, 47
	s_add_u32 s2, s2, s84
	s_add_u32 s60, s60, s84
